# softmax row-sum: 31-deep dependent add chain split into two interleaved chains (f32 sum reassociated), on top of the two-chain row-max
# baseline (speedup 1.0000x reference)
; #define SBAR() __builtin_amdgcn_sched_barrier(0)
; #define SLOAD(i, k0) do { sr_[i].vs0 = *reinterpret_cast<const bf16x8*>(&Vh[(size_t)((k0) + sr) * 128 + sc]); sr_[i].vs1 = *reinterpret_cast<const bf16x8*>(&Vh[(size_t)((k0) + 32 + sr) * 128 + sc]); \
;     sr_[i].ks0 = *reinterpret_cast<const bf16x8*>(&Kh[(size_t)((k0) + kr) * 64 + kc]); } while (0)
; DEV void finishSM(f32x16& p0, f32x16& p1, float alpha, float& l_reg, bf16x8& pa0, bf16x8& pa1, bf16x8& pa2, bf16x8& pa3) {
; #pragma unroll
;   for (int r = 0; r < 16; ++r) p1[r] = __builtin_amdgcn_exp2f(p1[r]);
;   float ps = 0;
; #pragma unroll
;   for (int r = 0; r < 16; ++r) ps += p0[r];
; #pragma unroll
;   for (int r = 0; r < 16; ++r) ps += p1[r];
;   { auto rr = __builtin_amdgcn_permlane32_swap(__float_as_uint(ps), __float_as_uint(ps), false, false);
;     ps = __uint_as_float(rr[0]) + __uint_as_float(rr[1]); }
;   l_reg = l_reg * alpha + ps;
; DEV void attn_pass(const u16* __restrict__ Qb, const u16* __restrict__ Kh, const u16* __restrict__ Vh, int seq, f32x16* o, float* rli) {
;     ...
;     SBAR(); qkt(pB0, pB1, K_lds + b0 * AT_SHM_K, qr, r32, hi);
;     finishSM(pA0, pA1, alA, l_reg, pa0, pa1, pa2, pa3); SBAR();
;     SLOAD(SO, (j + 2) * 64); SBAR();
;     pv_d0(o, vb0 + bm1 * AT_SHM_V, pa0, pa1, pa2, pa3); partialSM(pB0, pB1, m_reg, mnB, alB);
.LBB0_70:
	s_mul_hi_u32 s1, s9, 0xaaaaaaab
	s_lshr_b32 s1, s1, 1
	s_mul_i32 s1, s1, 0xc000
	v_subrev_u32_e32 v190, s1, v184
	s_mul_hi_u32 s1, s51, 0xaaaaaaab
	s_mul_hi_u32 s0, s66, 0xaaaaaaab
	s_lshr_b32 s12, s1, 1
	s_lshr_b32 s0, s0, 1
	s_mul_i32 s1, s12, 0x6000
	s_mul_i32 s15, s0, 0x6000
	v_subrev_u32_e32 v64, s1, v198
	s_mul_i32 s0, s0, 0xc000
	v_subrev_u32_e32 v216, s15, v180
	v_subrev_u32_e32 v164, s1, v200
	v_subrev_u32_e32 v217, s0, v203
	v_subrev_u32_e32 v218, s0, v204
	v_subrev_u32_e32 v191, s1, v209
	v_subrev_u32_e32 v192, s1, v210
	v_add_u32_e32 v141, s14, v181
	v_add_u32_e32 v68, v141, v64
	ds_read_b128 v[64:67], v68
	ds_read_b128 v[68:71], v68 offset:4096
	v_add_u32_e32 v186, v141, v164
	ds_read_b128 v[164:167], v186
	ds_read_b128 v[186:189], v186 offset:4096
	s_waitcnt vmcnt(0)
	v_add_u32_e32 v72, s8, v202
	v_add_u32_e32 v73, v72, v218
	ds_write_b128 v73, v[116:119]
	v_add_u32_e32 v73, v72, v217
	s_add_i32 s13, s14, 0
	ds_write_b128 v73, v[112:115]
	v_add_u32_e32 v73, s13, v216
	ds_write_b128 v73, v[120:123]
	v_exp_f32_e32 v134, v134
	s_waitcnt lgkmcnt(6)
	v_mfma_f32_32x32x16_bf16 v[80:95], v[64:67], v[108:111], v[236:251]
	v_exp_f32_e32 v135, v135
	v_exp_f32_e32 v132, v132
	v_exp_f32_e32 v133, v133
	v_exp_f32_e32 v130, v130
	v_exp_f32_e32 v131, v131
	v_exp_f32_e32 v128, v128
	v_exp_f32_e32 v129, v129
	s_waitcnt lgkmcnt(5)
	v_mfma_f32_32x32x16_bf16 v[64:79], v[68:71], v[108:111], v[236:251]
	v_exp_f32_e32 v126, v126
	v_exp_f32_e32 v127, v127
	v_exp_f32_e32 v124, v124
	v_exp_f32_e32 v125, v125
	s_waitcnt lgkmcnt(4)
	v_mfma_f32_32x32x16_bf16 v[80:95], v[164:167], v[104:107], v[80:95]
	s_waitcnt lgkmcnt(3)
	v_mfma_f32_32x32x16_bf16 v[64:79], v[186:189], v[104:107], v[64:79]
	v_add_u32_e32 v186, v141, v191
	ds_read_b128 v[164:167], v186
	ds_read_b128 v[186:189], v186 offset:4096
	s_waitcnt lgkmcnt(1)
	v_mfma_f32_32x32x16_bf16 v[80:95], v[164:167], v[100:103], v[80:95]
	s_waitcnt lgkmcnt(0)
	v_mfma_f32_32x32x16_bf16 v[64:79], v[186:189], v[100:103], v[64:79]
	v_add_u32_e32 v186, v141, v192
	ds_read_b128 v[164:167], v186
	ds_read_b128 v[186:189], v186 offset:4096
	s_waitcnt lgkmcnt(1)
	v_mfma_f32_32x32x16_bf16 v[80:95], v[164:167], v[96:99], v[80:95]
	v_exp_f32_e32 v166, v136
	v_add_f32_e32 v136, v160, v150
	v_mov_b32_e32 v211, v151
	v_add_f32_e32 v136, v161, v136
	v_add_f32_e32 v211, v158, v211
	v_add_f32_e32 v136, v214, v136
	v_add_f32_e32 v211, v159, v211
	v_add_f32_e32 v136, v215, v136
	v_add_f32_e32 v211, v142, v211
	v_add_f32_e32 v136, v146, v136
	v_add_f32_e32 v211, v143, v211
	v_add_f32_e32 v136, v147, v136
	v_exp_f32_e32 v164, v138
	v_add_f32_e32 v211, v144, v211
	v_exp_f32_e32 v165, v139
	v_add_f32_e32 v136, v148, v136
	v_add_f32_e32 v211, v145, v211
	v_exp_f32_e32 v167, v137
	v_add_f32_e32 v136, v149, v136
	v_add_f32_e32 v211, v164, v211
	v_add_f32_e32 v136, v165, v136
	v_add_f32_e32 v211, v166, v211
	v_add_f32_e32 v136, v167, v136
	v_add_f32_e32 v211, v134, v211
	v_add_f32_e32 v136, v135, v136
	v_add_f32_e32 v211, v132, v211
	v_add_f32_e32 v136, v133, v136
	v_add_f32_e32 v211, v130, v211
	v_add_f32_e32 v136, v131, v136
	s_waitcnt lgkmcnt(0)
	v_mfma_f32_32x32x16_bf16 v[64:79], v[186:189], v[96:99], v[64:79]
	v_add_f32_e32 v211, v128, v211
	v_add_f32_e32 v136, v129, v136
	v_add_f32_e32 v211, v126, v211
	v_add_f32_e32 v136, v127, v136
	v_add_f32_e32 v211, v124, v211
	v_add_f32_e32 v136, v125, v136
	v_add_f32_e32 v211, v211, v136
	v_mov_b32_e32 v212, v211
	v_cvt_pk_bf16_f32 v136, v150, v160
	v_cvt_pk_bf16_f32 v138, v158, v214
	s_nop 1
	v_permlane32_swap_b32_e32 v211, v212
	v_cvt_pk_bf16_f32 v137, v151, v161
	v_cvt_pk_bf16_f32 v139, v159, v215
	v_permlane32_swap_b32_e32 v136, v138
	v_cvt_pk_bf16_f32 v142, v142, v146
	v_cvt_pk_bf16_f32 v143, v143, v147
	v_cvt_pk_bf16_f32 v144, v144, v148
	v_cvt_pk_bf16_f32 v145, v145, v149
	v_cvt_pk_bf16_f32 v146, v164, v165
	v_cvt_pk_bf16_f32 v147, v166, v167
	v_cvt_pk_bf16_f32 v148, v134, v135
	v_cvt_pk_bf16_f32 v149, v132, v133
	v_cvt_pk_bf16_f32 v164, v130, v131
	v_cvt_pk_bf16_f32 v165, v128, v129
	v_cvt_pk_bf16_f32 v166, v126, v127
	v_cvt_pk_bf16_f32 v167, v124, v125
	v_permlane32_swap_b32_e32 v137, v139
	v_permlane32_swap_b32_e32 v142, v144
	v_permlane32_swap_b32_e32 v143, v145
	v_permlane32_swap_b32_e32 v146, v148
	v_permlane32_swap_b32_e32 v147, v149
	v_permlane32_swap_b32_e32 v164, v166
	v_permlane32_swap_b32_e32 v165, v167
	v_lshl_add_u64 v[158:159], v[156:157], 0, s[82:83]
	v_add_co_u32_e32 v124, vcc, s94, v158
	v_lshl_add_u64 v[160:161], v[154:155], 0, s[82:83]
	s_nop 0
	v_addc_co_u32_e32 v125, vcc, 0, v159, vcc
	v_add_co_u32_e32 v128, vcc, s95, v158
	s_mov_b32 s0, 0x18606000
	s_nop 0
	v_addc_co_u32_e32 v129, vcc, 0, v159, vcc
	v_add_co_u32_e32 v132, vcc, s0, v160
	global_load_dwordx4 v[124:127], v[124:125], off
	s_nop 0
	global_load_dwordx4 v[128:131], v[128:129], off
	v_addc_co_u32_e32 v133, vcc, 0, v161, vcc
	global_load_dwordx4 v[132:135], v[132:133], off
	v_add_u32_e32 v150, s8, v190
	ds_read_b64_tr_b16 v[186:187], v150 offset:0
	ds_read_b64_tr_b16 v[188:189], v150 offset:0x800
	ds_read_b64_tr_b16 v[190:191], v150 offset:0x1000
	ds_read_b64_tr_b16 v[192:193], v150 offset:0x1800
	ds_read_b64_tr_b16 v[220:221], v150 offset:0x2000
	ds_read_b64_tr_b16 v[222:223], v150 offset:0x2800
	ds_read_b64_tr_b16 v[224:225], v150 offset:0x3000
	ds_read_b64_tr_b16 v[226:227], v150 offset:0x3800
	s_waitcnt lgkmcnt(0)
; #define SBAR() __builtin_amdgcn_sched_barrier(0)
; DEV void partialSM(f32x16& p0, f32x16& p1, float& m_reg, float& mn, float& alpha) {
;   constexpr float C = AT_SCALE * 1.4426950408889634f;
;   float pmax = p0[0];
; #pragma unroll
;   for (int r = 1; r < 16; ++r) pmax = fmaxf(pmax, p0[r]);
; #pragma unroll
;   for (int r = 0; r < 16; ++r) pmax = fmaxf(pmax, p1[r]);
;   { auto rr = __builtin_amdgcn_permlane32_swap(__float_as_uint(pmax), __float_as_uint(pmax), false, false);
;     pmax = fmaxf(__uint_as_float(rr[0]), __uint_as_float(rr[1])); }
;   if (__builtin_expect(__all(pmax - m_reg <= AT_THR / AT_SCALE), 1)) { mn = m_reg; alpha = 1.f; }
;   else { mn = fmaxf(m_reg, pmax); alpha = __builtin_amdgcn_exp2f((m_reg - mn) * C); m_reg = mn; }
; template <int D0> DEV void pv_one(f32x16& od, int vb, bf16x8 pa0, bf16x8 pa1, bf16x8 pa2, bf16x8 pa3) {
;   const s16x4 l0 = tr_read<v_rd_off(D0, 0, 0)>(vb), h0 = tr_read<v_rd_off(D0, 0, 1)>(vb), l1 = tr_read<v_rd_off(D0, 1, 0)>(vb), h1 = tr_read<v_rd_off(D0, 1, 1)>(vb);
;   const s16x4 l2 = tr_read<v_rd_off(D0, 2, 0)>(vb), h2 = tr_read<v_rd_off(D0, 2, 1)>(vb), l3 = tr_read<v_rd_off(D0, 3, 0)>(vb), h3 = tr_read<v_rd_off(D0, 3, 1)>(vb);
;   asm volatile("s_waitcnt lgkmcnt(0)" ::: "memory"); SBAR();
;     ...
;   od = __builtin_amdgcn_mfma_f32_32x32x16_bf16(pa0, PK(l0, h0), od, 0, 0, 0);
;   od = __builtin_amdgcn_mfma_f32_32x32x16_bf16(pa1, PK(l1, h1), od, 0, 0, 0);
;   od = __builtin_amdgcn_mfma_f32_32x32x16_bf16(pa2, PK(l2, h2), od, 0, 0, 0);
;   od = __builtin_amdgcn_mfma_f32_32x32x16_bf16(pa3, PK(l3, h3), od, 0, 0, 0);
;     ...
; }
; DEV void pv_d0(f32x16* o, int vb, bf16x8 pa0, bf16x8 pa1, bf16x8 pa2, bf16x8 pa3) {
;   pv_one<0>(o[0], vb, pa0, pa1, pa2, pa3); pv_one<1>(o[1], vb, pa0, pa1, pa2, pa3); pv_one<2>(o[2], vb, pa0, pa1, pa2, pa3); pv_one<3>(o[3], vb, pa0, pa1, pa2, pa3);
	s_nop 0
	v_mfma_f32_32x32x16_bf16 v[0:15], v[136:139], v[186:189], v[0:15]
	ds_read_b64_tr_b16 v[186:187], v150 offset:0x200
	ds_read_b64_tr_b16 v[188:189], v150 offset:0xa00
	v_mfma_f32_32x32x16_bf16 v[0:15], v[142:145], v[190:193], v[0:15]
	ds_read_b64_tr_b16 v[190:191], v150 offset:0x1200
	ds_read_b64_tr_b16 v[192:193], v150 offset:0x1a00
	v_mfma_f32_32x32x16_bf16 v[0:15], v[146:149], v[220:223], v[0:15]
	ds_read_b64_tr_b16 v[220:221], v150 offset:0x2200
	ds_read_b64_tr_b16 v[222:223], v150 offset:0x2a00
	v_mfma_f32_32x32x16_bf16 v[0:15], v[164:167], v[224:227], v[0:15]
	ds_read_b64_tr_b16 v[224:225], v150 offset:0x3200
	ds_read_b64_tr_b16 v[226:227], v150 offset:0x3a00
	s_waitcnt lgkmcnt(0)
	v_mfma_f32_32x32x16_bf16 v[48:63], v[136:139], v[186:189], v[48:63]
	ds_read_b64_tr_b16 v[186:187], v150 offset:0x400
	ds_read_b64_tr_b16 v[188:189], v150 offset:0xc00
	v_mfma_f32_32x32x16_bf16 v[48:63], v[142:145], v[190:193], v[48:63]
	ds_read_b64_tr_b16 v[190:191], v150 offset:0x1400
	ds_read_b64_tr_b16 v[192:193], v150 offset:0x1c00
	v_mfma_f32_32x32x16_bf16 v[48:63], v[146:149], v[220:223], v[48:63]
	ds_read_b64_tr_b16 v[220:221], v150 offset:0x2400
	ds_read_b64_tr_b16 v[222:223], v150 offset:0x2c00
	v_mfma_f32_32x32x16_bf16 v[48:63], v[164:167], v[224:227], v[48:63]
	ds_read_b64_tr_b16 v[224:225], v150 offset:0x3400
	ds_read_b64_tr_b16 v[226:227], v150 offset:0x3c00
	s_waitcnt lgkmcnt(0)
	v_mfma_f32_32x32x16_bf16 v[32:47], v[136:139], v[186:189], v[32:47]
	ds_read_b64_tr_b16 v[186:187], v150 offset:0x600
	ds_read_b64_tr_b16 v[188:189], v150 offset:0xe00
	v_mfma_f32_32x32x16_bf16 v[32:47], v[142:145], v[190:193], v[32:47]
	ds_read_b64_tr_b16 v[190:191], v150 offset:0x1600
	ds_read_b64_tr_b16 v[192:193], v150 offset:0x1e00
	v_mfma_f32_32x32x16_bf16 v[32:47], v[146:149], v[220:223], v[32:47]
	ds_read_b64_tr_b16 v[220:221], v150 offset:0x2600
	ds_read_b64_tr_b16 v[222:223], v150 offset:0x2e00
	v_mfma_f32_32x32x16_bf16 v[32:47], v[164:167], v[224:227], v[32:47]
	ds_read_b64_tr_b16 v[224:225], v150 offset:0x3600
	ds_read_b64_tr_b16 v[226:227], v150 offset:0x3e00
	s_waitcnt lgkmcnt(0)
	v_mfma_f32_32x32x16_bf16 v[16:31], v[136:139], v[186:189], v[16:31]
	v_max_f32_e32 v136, v80, v81
	v_max3_f32 v137, v64, v65, v66
	v_max3_f32 v136, v136, v82, v83
	v_max3_f32 v137, v137, v67, v68
	v_max3_f32 v136, v136, v84, v85
	v_max3_f32 v137, v137, v69, v70
	v_max3_f32 v136, v136, v86, v87
	v_max3_f32 v137, v137, v71, v72
	v_mfma_f32_32x32x16_bf16 v[16:31], v[142:145], v[190:193], v[16:31]
	v_max3_f32 v136, v136, v88, v89
	v_max3_f32 v137, v137, v73, v74
	v_max3_f32 v136, v136, v90, v91
	v_max3_f32 v137, v137, v75, v76
	v_max3_f32 v136, v136, v92, v93
	v_max3_f32 v137, v137, v77, v78
	v_max3_f32 v136, v136, v94, v95
	v_max3_f32 v136, v136, v137, v79
	v_mfma_f32_32x32x16_bf16 v[16:31], v[146:149], v[220:223], v[16:31]
	v_mov_b32_e32 v137, v136
	s_nop 1
	v_permlane32_swap_b32_e32 v136, v137
	v_max_f32_e32 v136, v136, v137
	v_cmp_ge_f32_e32 vcc, s18, v136
	v_mfma_f32_32x32x16_bf16 v[16:31], v[164:167], v[224:227], v[16:31]
	s_cmp_eq_u64 vcc, exec
	s_cselect_b64 s[0:1], -1, 0
	s_cbranch_scc1 .Lattn_fast1
	v_max_f32_e32 v136, 0, v136
	v_exp_f32_e64 v137, -v136

; #define SBAR() __builtin_amdgcn_sched_barrier(0)
; #define SLOAD(i, k0) do { sr_[i].vs0 = *reinterpret_cast<const bf16x8*>(&Vh[(size_t)((k0) + sr) * 128 + sc]); sr_[i].vs1 = *reinterpret_cast<const bf16x8*>(&Vh[(size_t)((k0) + 32 + sr) * 128 + sc]); \
;     sr_[i].ks0 = *reinterpret_cast<const bf16x8*>(&Kh[(size_t)((k0) + kr) * 64 + kc]); } while (0)
; #define RESC(a) do { if (__any((a) < 1.f)) { if (hi == 0) al_l[r32] = (a); asm volatile("s_waitcnt lgkmcnt(0)" ::: "memory"); \
;     for (int d = 0; d < 4; ++d) for (int r = 0; r < 16; ++r) o[d][r] *= al_l[crow(r, hi)]; } } while (0)
; DEV void finishSM(f32x16& p0, f32x16& p1, float alpha, float& l_reg, bf16x8& pa0, bf16x8& pa1, bf16x8& pa2, bf16x8& pa3) {
; #pragma unroll
;   for (int r = 0; r < 16; ++r) p1[r] = __builtin_amdgcn_exp2f(p1[r]);
;   float ps = 0;
; #pragma unroll
;   for (int r = 0; r < 16; ++r) ps += p0[r];
; #pragma unroll
;   for (int r = 0; r < 16; ++r) ps += p1[r];
;   { auto rr = __builtin_amdgcn_permlane32_swap(__float_as_uint(ps), __float_as_uint(ps), false, false);
;     ps = __uint_as_float(rr[0]) + __uint_as_float(rr[1]); }
;   l_reg = l_reg * alpha + ps;
;     ...
;   PK4(p0, 0, pa0); PK4(p0, 8, pa1); PK4(p1, 0, pa2); PK4(p1, 8, pa3);
; DEV void attn_pass(const u16* __restrict__ Qb, const u16* __restrict__ Kh, const u16* __restrict__ Vh, int seq, f32x16* o, float* rli) {
;     ...
;     RESC(alB); __syncthreads();
;     SBAR(); qkt(pA0, pA1, K_lds + b1 * AT_SHM_K, qr, r32, hi);
;     finishSM(pB0, pB1, alB, l_reg, pa0, pa1, pa2, pa3); SBAR();
;     if (j + 3 < NT) SLOAD(SE, (j + 3) * 64); SBAR();
.LBB0_74:
	v_subrev_u32_e32 v137, s15, v183
	v_subrev_u32_e32 v138, s15, v185
	v_subrev_u32_e32 v146, s15, v199
	v_subrev_u32_e32 v147, s15, v201
	v_mov_b32_e32 v149, v64
	v_mov_b32_e32 v150, v65
	v_mov_b32_e32 v151, v66
	v_mov_b32_e32 v164, v67
	v_mov_b32_e32 v165, v68
	v_mov_b32_e32 v166, v69
	v_mov_b32_e32 v167, v70
	v_mov_b32_e32 v186, v71
	v_mov_b32_e32 v187, v72
	v_mov_b32_e32 v188, v73
	v_mov_b32_e32 v189, v74
	v_mov_b32_e32 v190, v75
	v_mov_b32_e32 v191, v76
	v_mov_b32_e32 v192, v77
	v_mov_b32_e32 v193, v78
	v_mov_b32_e32 v148, v79
	v_exp_f32_e32 v194, v80
	v_exp_f32_e32 v195, v81
	v_exp_f32_e32 v218, v82
	v_exp_f32_e32 v219, v83
	v_exp_f32_e32 v220, v84
	v_exp_f32_e32 v221, v85
	v_exp_f32_e32 v222, v86
	v_exp_f32_e32 v223, v87
	v_exp_f32_e32 v224, v88
	v_exp_f32_e32 v225, v89
	v_exp_f32_e32 v226, v90
	v_exp_f32_e32 v227, v91
	v_exp_f32_e32 v228, v92
	v_exp_f32_e32 v229, v93
	v_exp_f32_e32 v230, v94
	v_exp_f32_e32 v231, v95
	s_waitcnt lgkmcnt(0)
	s_barrier
	v_add_u32_e32 v68, v141, v137
	ds_read_b128 v[64:67], v68
	ds_read_b128 v[68:71], v68 offset:4096
	v_add_u32_e32 v140, v141, v138
	ds_read_b128 v[136:139], v140
	ds_read_b128 v[142:145], v140 offset:4096
	v_add_u32_e32 v140, v141, v146
	s_waitcnt vmcnt(0)
	s_mul_hi_u32 s0, s50, 0xaaaaaaab
	s_lshr_b32 s0, s0, 1
	s_mul_i32 s1, s0, 0x6000
	s_mul_i32 s0, s0, 0xc000
	v_subrev_u32_e32 v72, s0, v207
	v_add_u32_e32 v72, v214, v72
	ds_write_b128 v72, v[124:127]
	v_subrev_u32_e32 v72, s0, v206
	v_add_u32_e32 v72, v214, v72
	ds_write_b128 v72, v[128:131]
	v_subrev_u32_e32 v72, s1, v205
	v_add_u32_e32 v72, s13, v72
	ds_write_b128 v72, v[132:135]
	s_waitcnt lgkmcnt(6)
	v_mfma_f32_32x32x16_bf16 v[80:95], v[64:67], v[108:111], v[236:251]
	v_exp_f32_e32 v146, v151
	v_exp_f32_e32 v151, v167
	v_exp_f32_e32 v167, v189
	v_exp_f32_e32 v189, v193
	s_waitcnt lgkmcnt(5)
	v_mfma_f32_32x32x16_bf16 v[64:79], v[68:71], v[108:111], v[236:251]
	s_waitcnt lgkmcnt(4)
	v_mfma_f32_32x32x16_bf16 v[80:95], v[136:139], v[104:107], v[80:95]
	s_waitcnt lgkmcnt(3)
	v_mfma_f32_32x32x16_bf16 v[64:79], v[142:145], v[104:107], v[64:79]
	ds_read_b128 v[136:139], v140
	ds_read_b128 v[142:145], v140 offset:4096
	v_add_u32_e32 v140, v141, v147
	v_exp_f32_e32 v147, v164
	v_exp_f32_e32 v164, v186
	v_exp_f32_e32 v186, v190
	v_exp_f32_e32 v190, v148
	s_waitcnt lgkmcnt(1)
	v_mfma_f32_32x32x16_bf16 v[80:95], v[136:139], v[100:103], v[80:95]
	s_waitcnt lgkmcnt(0)
	v_mfma_f32_32x32x16_bf16 v[64:79], v[142:145], v[100:103], v[64:79]
	ds_read_b128 v[136:139], v140
	ds_read_b128 v[140:143], v140 offset:4096
	v_exp_f32_e32 v144, v149
	v_exp_f32_e32 v145, v150
	v_exp_f32_e32 v149, v165
	v_exp_f32_e32 v150, v166
	v_exp_f32_e32 v165, v187
	v_exp_f32_e32 v166, v188
	s_waitcnt lgkmcnt(1)
	v_mfma_f32_32x32x16_bf16 v[80:95], v[136:139], v[96:99], v[80:95]
	v_add_f32_e32 v136, v195, v194
	v_mov_b32_e32 v216, v218
	v_add_f32_e32 v136, v219, v136
	v_add_f32_e32 v216, v220, v216
	v_add_f32_e32 v136, v221, v136
	v_add_f32_e32 v216, v222, v216
	v_add_f32_e32 v136, v223, v136
	v_add_f32_e32 v216, v224, v216
	v_add_f32_e32 v136, v225, v136
	v_add_f32_e32 v216, v226, v216
	v_add_f32_e32 v136, v227, v136
	v_add_f32_e32 v216, v228, v216
	v_add_f32_e32 v136, v229, v136
	v_add_f32_e32 v216, v230, v216
	v_add_f32_e32 v136, v231, v136
	v_add_f32_e32 v216, v144, v216
	v_add_f32_e32 v136, v145, v136
	v_add_f32_e32 v216, v146, v216
	v_add_f32_e32 v136, v147, v136
	v_add_f32_e32 v216, v149, v216
	v_add_f32_e32 v136, v150, v136
	v_add_f32_e32 v216, v151, v216
	v_add_f32_e32 v136, v164, v136
	v_exp_f32_e32 v187, v191
	v_add_f32_e32 v216, v165, v216
	v_exp_f32_e32 v188, v192
	v_add_f32_e32 v136, v166, v136
	s_waitcnt lgkmcnt(0)
	v_mfma_f32_32x32x16_bf16 v[64:79], v[140:143], v[96:99], v[64:79]
	v_add_f32_e32 v216, v167, v216
	v_add_f32_e32 v136, v186, v136
	v_add_f32_e32 v216, v187, v216
	v_add_f32_e32 v136, v188, v136
	v_add_f32_e32 v216, v189, v216
	v_add_f32_e32 v136, v190, v136
	v_add_f32_e32 v216, v216, v136
	v_mov_b32_e32 v217, v216
	v_cvt_pk_bf16_f32 v136, v194, v195
	v_cvt_pk_bf16_f32 v137, v218, v219
	v_cvt_pk_bf16_f32 v138, v220, v221
	v_cvt_pk_bf16_f32 v139, v222, v223
	v_cvt_pk_bf16_f32 v140, v224, v225
	v_cvt_pk_bf16_f32 v141, v226, v227
	v_cvt_pk_bf16_f32 v142, v228, v229
	v_cvt_pk_bf16_f32 v143, v230, v231
	v_cvt_pk_bf16_f32 v144, v144, v145
	v_cvt_pk_bf16_f32 v145, v146, v147
	v_cvt_pk_bf16_f32 v146, v149, v150
	v_cvt_pk_bf16_f32 v147, v151, v164
	v_cvt_pk_bf16_f32 v148, v165, v166
	v_cvt_pk_bf16_f32 v149, v167, v186
	v_cvt_pk_bf16_f32 v150, v187, v188
	v_cvt_pk_bf16_f32 v151, v189, v190
	s_nop 1
	v_permlane32_swap_b32_e32 v216, v217
	v_permlane32_swap_b32_e32 v136, v138
	v_permlane32_swap_b32_e32 v137, v139
	v_permlane32_swap_b32_e32 v140, v142
	v_permlane32_swap_b32_e32 v141, v143
	v_permlane32_swap_b32_e32 v144, v146
	v_permlane32_swap_b32_e32 v145, v147
	v_permlane32_swap_b32_e32 v148, v150
	v_permlane32_swap_b32_e32 v149, v151
	s_cmp_ge_u32 s45, s44
	s_cselect_b64 s[10:11], -1, 0
	s_and_b64 vcc, exec, s[10:11]
	s_cbranch_vccnz .LBB0_76
	v_add_co_u32_e32 v112, vcc, 0x1a810000, v158
	s_nop 1
	v_addc_co_u32_e32 v113, vcc, 0, v159, vcc
	v_add_co_u32_e32 v114, vcc, 0x1a812000, v158
	s_nop 1
	v_addc_co_u32_e32 v115, vcc, 0, v159, vcc
	v_add_co_u32_e32 v120, vcc, 0x18608000, v160
	global_load_dwordx4 v[116:119], v[112:113], off
	s_nop 0
	global_load_dwordx4 v[112:115], v[114:115], off
	v_addc_co_u32_e32 v121, vcc, 0, v161, vcc
	global_load_dwordx4 v[120:123], v[120:121], off

; #define SBAR() __builtin_amdgcn_sched_barrier(0)
; #define SLOAD(i, k0) do { sr_[i].vs0 = *reinterpret_cast<const bf16x8*>(&Vh[(size_t)((k0) + sr) * 128 + sc]); sr_[i].vs1 = *reinterpret_cast<const bf16x8*>(&Vh[(size_t)((k0) + 32 + sr) * 128 + sc]); \
;     sr_[i].ks0 = *reinterpret_cast<const bf16x8*>(&Kh[(size_t)((k0) + kr) * 64 + kc]); } while (0)
; DEV void finishSM(f32x16& p0, f32x16& p1, float alpha, float& l_reg, bf16x8& pa0, bf16x8& pa1, bf16x8& pa2, bf16x8& pa3) {
; #pragma unroll
;   for (int r = 0; r < 16; ++r) p1[r] = __builtin_amdgcn_exp2f(p1[r]);
;   float ps = 0;
; #pragma unroll
;   for (int r = 0; r < 16; ++r) ps += p0[r];
; #pragma unroll
;   for (int r = 0; r < 16; ++r) ps += p1[r];
;   { auto rr = __builtin_amdgcn_permlane32_swap(__float_as_uint(ps), __float_as_uint(ps), false, false);
;     ps = __uint_as_float(rr[0]) + __uint_as_float(rr[1]); }
;   l_reg = l_reg * alpha + ps;
;     ...
;   PK4(p0, 0, pa0); PK4(p0, 8, pa1); PK4(p1, 0, pa2); PK4(p1, 8, pa3);
; DEV void attn_pass(const u16* __restrict__ Qb, const u16* __restrict__ Kh, const u16* __restrict__ Vh, int seq, f32x16* o, float* rli) {
;     ...
;     SBAR(); qkt(pB0, pB1, K_lds + b0 * AT_SHM_K, qr, r32, hi);
;     finishSM(pA0, pA1, alA, l_reg, pa0, pa1, pa2, pa3); SBAR();
;     SLOAD(SO, (j + 2) * 64); SBAR();
;     pv_d0(o, vb0 + bm1 * AT_SHM_V, pa0, pa1, pa2, pa3); partialSM(pB0, pB1, m_reg, mnB, alB);
.LBB0_90:
	s_mul_hi_u32 s1, s9, 0xaaaaaaab
	s_lshr_b32 s1, s1, 1
	s_mul_i32 s1, s1, 0xc000
	v_subrev_u32_e32 v190, s1, v199
	s_mul_hi_u32 s1, s47, 0xaaaaaaab
	s_mul_hi_u32 s0, s46, 0xaaaaaaab
	s_lshr_b32 s12, s1, 1
	s_lshr_b32 s0, s0, 1
	s_mul_i32 s1, s12, 0x6000
	s_mul_i32 s15, s0, 0x6000
	v_subrev_u32_e32 v64, s1, v201
	s_mul_i32 s0, s0, 0xc000
	v_subrev_u32_e32 v219, s15, v183
	v_subrev_u32_e32 v164, s1, v203
	v_subrev_u32_e32 v220, s0, v206
	v_subrev_u32_e32 v221, s0, v207
	v_subrev_u32_e32 v191, s1, v212
	v_subrev_u32_e32 v192, s1, v213
	v_add_u32_e32 v141, s14, v184
	v_add_u32_e32 v68, v141, v64
	ds_read_b128 v[64:67], v68
	ds_read_b128 v[68:71], v68 offset:4096
	v_add_u32_e32 v186, v141, v164
	ds_read_b128 v[164:167], v186
	ds_read_b128 v[186:189], v186 offset:4096
	s_waitcnt vmcnt(0)
	v_add_u32_e32 v72, s8, v205
	v_add_u32_e32 v73, v72, v221
	ds_write_b128 v73, v[116:119]
	v_add_u32_e32 v73, v72, v220
	s_add_i32 s13, s14, 0
	ds_write_b128 v73, v[112:115]
	v_add_u32_e32 v73, s13, v219
	ds_write_b128 v73, v[120:123]
	v_exp_f32_e32 v134, v134
	s_waitcnt lgkmcnt(6)
	v_mfma_f32_32x32x16_bf16 v[80:95], v[64:67], v[108:111], v[236:251]
	v_exp_f32_e32 v135, v135
	v_exp_f32_e32 v132, v132
	v_exp_f32_e32 v133, v133
	v_exp_f32_e32 v130, v130
	v_exp_f32_e32 v131, v131
	v_exp_f32_e32 v128, v128
	v_exp_f32_e32 v129, v129
	s_waitcnt lgkmcnt(5)
	v_mfma_f32_32x32x16_bf16 v[64:79], v[68:71], v[108:111], v[236:251]
	v_exp_f32_e32 v126, v126
	v_exp_f32_e32 v127, v127
	v_exp_f32_e32 v124, v124
	v_exp_f32_e32 v125, v125
	s_waitcnt lgkmcnt(4)
	v_mfma_f32_32x32x16_bf16 v[80:95], v[164:167], v[104:107], v[80:95]
	s_waitcnt lgkmcnt(3)
	v_mfma_f32_32x32x16_bf16 v[64:79], v[186:189], v[104:107], v[64:79]
	v_add_u32_e32 v186, v141, v191
	ds_read_b128 v[164:167], v186
	ds_read_b128 v[186:189], v186 offset:4096
	s_waitcnt lgkmcnt(1)
	v_mfma_f32_32x32x16_bf16 v[80:95], v[164:167], v[100:103], v[80:95]
	s_waitcnt lgkmcnt(0)
	v_mfma_f32_32x32x16_bf16 v[64:79], v[186:189], v[100:103], v[64:79]
	v_add_u32_e32 v186, v141, v192
	ds_read_b128 v[164:167], v186
	ds_read_b128 v[186:189], v186 offset:4096
	s_waitcnt lgkmcnt(1)
	v_mfma_f32_32x32x16_bf16 v[80:95], v[164:167], v[96:99], v[80:95]
	v_exp_f32_e32 v166, v136
	v_add_f32_e32 v136, v170, v150
	v_mov_b32_e32 v214, v151
	v_add_f32_e32 v136, v171, v136
	v_add_f32_e32 v214, v168, v214
	v_add_f32_e32 v136, v217, v136
	v_add_f32_e32 v214, v169, v214
	v_add_f32_e32 v136, v218, v136
	v_add_f32_e32 v214, v142, v214
	v_add_f32_e32 v136, v146, v136
	v_add_f32_e32 v214, v143, v214
	v_add_f32_e32 v136, v147, v136
	v_exp_f32_e32 v164, v138
	v_add_f32_e32 v214, v144, v214
	v_exp_f32_e32 v165, v139
	v_add_f32_e32 v136, v148, v136
	v_add_f32_e32 v214, v145, v214
	v_exp_f32_e32 v167, v137
	v_add_f32_e32 v136, v149, v136
	v_add_f32_e32 v214, v164, v214
	v_add_f32_e32 v136, v165, v136
	v_add_f32_e32 v214, v166, v214
	v_add_f32_e32 v136, v167, v136
	v_add_f32_e32 v214, v134, v214
	v_add_f32_e32 v136, v135, v136
	v_add_f32_e32 v214, v132, v214
	v_add_f32_e32 v136, v133, v136
	v_add_f32_e32 v214, v130, v214
	v_add_f32_e32 v136, v131, v136
	s_waitcnt lgkmcnt(0)
	v_mfma_f32_32x32x16_bf16 v[64:79], v[186:189], v[96:99], v[64:79]
	v_add_f32_e32 v214, v128, v214
	v_add_f32_e32 v136, v129, v136
	v_add_f32_e32 v214, v126, v214
	v_add_f32_e32 v136, v127, v136
	v_add_f32_e32 v214, v124, v214
	v_add_f32_e32 v136, v125, v136
	v_add_f32_e32 v214, v214, v136
	v_mov_b32_e32 v215, v214
	v_cvt_pk_bf16_f32 v136, v150, v170
	v_cvt_pk_bf16_f32 v138, v168, v217
	s_nop 1
	v_permlane32_swap_b32_e32 v214, v215
	v_cvt_pk_bf16_f32 v137, v151, v171
	v_cvt_pk_bf16_f32 v139, v169, v218
	v_permlane32_swap_b32_e32 v136, v138
	v_cvt_pk_bf16_f32 v142, v142, v146
	v_cvt_pk_bf16_f32 v143, v143, v147
	v_cvt_pk_bf16_f32 v144, v144, v148
	v_cvt_pk_bf16_f32 v145, v145, v149
	v_cvt_pk_bf16_f32 v146, v164, v165
	v_cvt_pk_bf16_f32 v147, v166, v167
	v_cvt_pk_bf16_f32 v148, v134, v135
	v_cvt_pk_bf16_f32 v149, v132, v133
	v_cvt_pk_bf16_f32 v164, v130, v131
	v_cvt_pk_bf16_f32 v165, v128, v129
	v_cvt_pk_bf16_f32 v166, v126, v127
	v_cvt_pk_bf16_f32 v167, v124, v125
	v_permlane32_swap_b32_e32 v137, v139
	v_permlane32_swap_b32_e32 v142, v144
	v_permlane32_swap_b32_e32 v143, v145
	v_permlane32_swap_b32_e32 v146, v148
	v_permlane32_swap_b32_e32 v147, v149
	v_permlane32_swap_b32_e32 v164, v166
	v_permlane32_swap_b32_e32 v165, v167
	v_lshl_add_u64 v[168:169], v[160:161], 0, s[82:83]
	v_add_co_u32_e32 v124, vcc, s94, v168
	v_lshl_add_u64 v[170:171], v[158:159], 0, s[82:83]
	s_nop 0
	v_addc_co_u32_e32 v125, vcc, 0, v169, vcc
	v_add_co_u32_e32 v128, vcc, s95, v168
	s_mov_b32 s0, 0x1868e000
	s_nop 0
	v_addc_co_u32_e32 v129, vcc, 0, v169, vcc
	v_add_co_u32_e32 v132, vcc, s0, v170
	global_load_dwordx4 v[124:127], v[124:125], off
	s_nop 0
	global_load_dwordx4 v[128:131], v[128:129], off
	v_addc_co_u32_e32 v133, vcc, 0, v171, vcc
	global_load_dwordx4 v[132:135], v[132:133], off
	v_add_u32_e32 v150, s8, v190
	ds_read_b64_tr_b16 v[186:187], v150 offset:0
	ds_read_b64_tr_b16 v[188:189], v150 offset:0x800
	ds_read_b64_tr_b16 v[190:191], v150 offset:0x1000
	ds_read_b64_tr_b16 v[192:193], v150 offset:0x1800
	ds_read_b64_tr_b16 v[222:223], v150 offset:0x2000
	ds_read_b64_tr_b16 v[224:225], v150 offset:0x2800
	ds_read_b64_tr_b16 v[226:227], v150 offset:0x3000
	ds_read_b64_tr_b16 v[228:229], v150 offset:0x3800
	s_waitcnt lgkmcnt(0)
; #define SBAR() __builtin_amdgcn_sched_barrier(0)
; DEV void partialSM(f32x16& p0, f32x16& p1, float& m_reg, float& mn, float& alpha) {
;   constexpr float C = AT_SCALE * 1.4426950408889634f;
;   float pmax = p0[0];
; #pragma unroll
;   for (int r = 1; r < 16; ++r) pmax = fmaxf(pmax, p0[r]);
; #pragma unroll
;   for (int r = 0; r < 16; ++r) pmax = fmaxf(pmax, p1[r]);
;   { auto rr = __builtin_amdgcn_permlane32_swap(__float_as_uint(pmax), __float_as_uint(pmax), false, false);
;     pmax = fmaxf(__uint_as_float(rr[0]), __uint_as_float(rr[1])); }
;   if (__builtin_expect(__all(pmax - m_reg <= AT_THR / AT_SCALE), 1)) { mn = m_reg; alpha = 1.f; }
;   else { mn = fmaxf(m_reg, pmax); alpha = __builtin_amdgcn_exp2f((m_reg - mn) * C); m_reg = mn; }
; template <int D0> DEV void pv_one(f32x16& od, int vb, bf16x8 pa0, bf16x8 pa1, bf16x8 pa2, bf16x8 pa3) {
;   const s16x4 l0 = tr_read<v_rd_off(D0, 0, 0)>(vb), h0 = tr_read<v_rd_off(D0, 0, 1)>(vb), l1 = tr_read<v_rd_off(D0, 1, 0)>(vb), h1 = tr_read<v_rd_off(D0, 1, 1)>(vb);
;   const s16x4 l2 = tr_read<v_rd_off(D0, 2, 0)>(vb), h2 = tr_read<v_rd_off(D0, 2, 1)>(vb), l3 = tr_read<v_rd_off(D0, 3, 0)>(vb), h3 = tr_read<v_rd_off(D0, 3, 1)>(vb);
;   asm volatile("s_waitcnt lgkmcnt(0)" ::: "memory"); SBAR();
;     ...
;   od = __builtin_amdgcn_mfma_f32_32x32x16_bf16(pa0, PK(l0, h0), od, 0, 0, 0);
;   od = __builtin_amdgcn_mfma_f32_32x32x16_bf16(pa1, PK(l1, h1), od, 0, 0, 0);
;   od = __builtin_amdgcn_mfma_f32_32x32x16_bf16(pa2, PK(l2, h2), od, 0, 0, 0);
;   od = __builtin_amdgcn_mfma_f32_32x32x16_bf16(pa3, PK(l3, h3), od, 0, 0, 0);
;     ...
; }
; DEV void pv_d0(f32x16* o, int vb, bf16x8 pa0, bf16x8 pa1, bf16x8 pa2, bf16x8 pa3) {
;   pv_one<0>(o[0], vb, pa0, pa1, pa2, pa3); pv_one<1>(o[1], vb, pa0, pa1, pa2, pa3); pv_one<2>(o[2], vb, pa0, pa1, pa2, pa3); pv_one<3>(o[3], vb, pa0, pa1, pa2, pa3);
	s_nop 0
	v_mfma_f32_32x32x16_bf16 v[0:15], v[136:139], v[186:189], v[0:15]
	ds_read_b64_tr_b16 v[186:187], v150 offset:0x200
	ds_read_b64_tr_b16 v[188:189], v150 offset:0xa00
	v_mfma_f32_32x32x16_bf16 v[0:15], v[142:145], v[190:193], v[0:15]
	ds_read_b64_tr_b16 v[190:191], v150 offset:0x1200
	ds_read_b64_tr_b16 v[192:193], v150 offset:0x1a00
	v_mfma_f32_32x32x16_bf16 v[0:15], v[146:149], v[222:225], v[0:15]
	ds_read_b64_tr_b16 v[222:223], v150 offset:0x2200
	ds_read_b64_tr_b16 v[224:225], v150 offset:0x2a00
	v_mfma_f32_32x32x16_bf16 v[0:15], v[164:167], v[226:229], v[0:15]
	ds_read_b64_tr_b16 v[226:227], v150 offset:0x3200
	ds_read_b64_tr_b16 v[228:229], v150 offset:0x3a00
	s_waitcnt lgkmcnt(0)
	v_mfma_f32_32x32x16_bf16 v[48:63], v[136:139], v[186:189], v[48:63]
	ds_read_b64_tr_b16 v[186:187], v150 offset:0x400
	ds_read_b64_tr_b16 v[188:189], v150 offset:0xc00
	v_mfma_f32_32x32x16_bf16 v[48:63], v[142:145], v[190:193], v[48:63]
	ds_read_b64_tr_b16 v[190:191], v150 offset:0x1400
	ds_read_b64_tr_b16 v[192:193], v150 offset:0x1c00
	v_mfma_f32_32x32x16_bf16 v[48:63], v[146:149], v[222:225], v[48:63]
	ds_read_b64_tr_b16 v[222:223], v150 offset:0x2400
	ds_read_b64_tr_b16 v[224:225], v150 offset:0x2c00
	v_mfma_f32_32x32x16_bf16 v[48:63], v[164:167], v[226:229], v[48:63]
	ds_read_b64_tr_b16 v[226:227], v150 offset:0x3400
	ds_read_b64_tr_b16 v[228:229], v150 offset:0x3c00
	s_waitcnt lgkmcnt(0)
	v_mfma_f32_32x32x16_bf16 v[32:47], v[136:139], v[186:189], v[32:47]
	ds_read_b64_tr_b16 v[186:187], v150 offset:0x600
	ds_read_b64_tr_b16 v[188:189], v150 offset:0xe00
	v_mfma_f32_32x32x16_bf16 v[32:47], v[142:145], v[190:193], v[32:47]
	ds_read_b64_tr_b16 v[190:191], v150 offset:0x1600
	ds_read_b64_tr_b16 v[192:193], v150 offset:0x1e00
	v_mfma_f32_32x32x16_bf16 v[32:47], v[146:149], v[222:225], v[32:47]
	ds_read_b64_tr_b16 v[222:223], v150 offset:0x2600
	ds_read_b64_tr_b16 v[224:225], v150 offset:0x2e00
	v_mfma_f32_32x32x16_bf16 v[32:47], v[164:167], v[226:229], v[32:47]
	ds_read_b64_tr_b16 v[226:227], v150 offset:0x3600
	ds_read_b64_tr_b16 v[228:229], v150 offset:0x3e00
	s_waitcnt lgkmcnt(0)
	v_mfma_f32_32x32x16_bf16 v[16:31], v[136:139], v[186:189], v[16:31]
	v_max_f32_e32 v136, v80, v81
	v_max3_f32 v137, v64, v65, v66
	v_max3_f32 v136, v136, v82, v83
	v_max3_f32 v137, v137, v67, v68
	v_max3_f32 v136, v136, v84, v85
	v_max3_f32 v137, v137, v69, v70
	v_max3_f32 v136, v136, v86, v87
	v_max3_f32 v137, v137, v71, v72
	v_mfma_f32_32x32x16_bf16 v[16:31], v[142:145], v[190:193], v[16:31]
	v_max3_f32 v136, v136, v88, v89
	v_max3_f32 v137, v137, v73, v74
	v_max3_f32 v136, v136, v90, v91
	v_max3_f32 v137, v137, v75, v76
	v_max3_f32 v136, v136, v92, v93
	v_max3_f32 v137, v137, v77, v78
	v_max3_f32 v136, v136, v94, v95
	v_max3_f32 v136, v136, v137, v79
	v_mfma_f32_32x32x16_bf16 v[16:31], v[146:149], v[222:225], v[16:31]
	v_mov_b32_e32 v137, v136
	s_nop 1
	v_permlane32_swap_b32_e32 v136, v137
	v_max_f32_e32 v136, v136, v137
	v_cmp_ge_f32_e32 vcc, s18, v136
	v_mfma_f32_32x32x16_bf16 v[16:31], v[164:167], v[226:229], v[16:31]
	s_cmp_eq_u64 vcc, exec
	s_cselect_b64 s[0:1], -1, 0
	s_cbranch_scc1 .Lattn_fast3
	v_max_f32_e32 v136, 0, v136
	v_exp_f32_e64 v137, -v136

; #define SBAR() __builtin_amdgcn_sched_barrier(0)
; #define SLOAD(i, k0) do { sr_[i].vs0 = *reinterpret_cast<const bf16x8*>(&Vh[(size_t)((k0) + sr) * 128 + sc]); sr_[i].vs1 = *reinterpret_cast<const bf16x8*>(&Vh[(size_t)((k0) + 32 + sr) * 128 + sc]); \
;     sr_[i].ks0 = *reinterpret_cast<const bf16x8*>(&Kh[(size_t)((k0) + kr) * 64 + kc]); } while (0)
; #define RESC(a) do { if (__any((a) < 1.f)) { if (hi == 0) al_l[r32] = (a); asm volatile("s_waitcnt lgkmcnt(0)" ::: "memory"); \
;     for (int d = 0; d < 4; ++d) for (int r = 0; r < 16; ++r) o[d][r] *= al_l[crow(r, hi)]; } } while (0)
; DEV void finishSM(f32x16& p0, f32x16& p1, float alpha, float& l_reg, bf16x8& pa0, bf16x8& pa1, bf16x8& pa2, bf16x8& pa3) {
; #pragma unroll
;   for (int r = 0; r < 16; ++r) p1[r] = __builtin_amdgcn_exp2f(p1[r]);
;   float ps = 0;
; #pragma unroll
;   for (int r = 0; r < 16; ++r) ps += p0[r];
; #pragma unroll
;   for (int r = 0; r < 16; ++r) ps += p1[r];
;   { auto rr = __builtin_amdgcn_permlane32_swap(__float_as_uint(ps), __float_as_uint(ps), false, false);
;     ps = __uint_as_float(rr[0]) + __uint_as_float(rr[1]); }
;   l_reg = l_reg * alpha + ps;
;     ...
;   PK4(p0, 0, pa0); PK4(p0, 8, pa1); PK4(p1, 0, pa2); PK4(p1, 8, pa3);
; DEV void attn_pass(const u16* __restrict__ Qb, const u16* __restrict__ Kh, const u16* __restrict__ Vh, int seq, f32x16* o, float* rli) {
;     ...
;     RESC(alB); __syncthreads();
;     SBAR(); qkt(pA0, pA1, K_lds + b1 * AT_SHM_K, qr, r32, hi);
;     finishSM(pB0, pB1, alB, l_reg, pa0, pa1, pa2, pa3); SBAR();
;     if (j + 3 < NT) SLOAD(SE, (j + 3) * 64); SBAR();
.LBB0_94:
	v_subrev_u32_e32 v137, s15, v198
	v_subrev_u32_e32 v138, s15, v200
	v_subrev_u32_e32 v146, s15, v202
	v_subrev_u32_e32 v147, s15, v204
	v_mov_b32_e32 v149, v64
	v_mov_b32_e32 v150, v65
	v_mov_b32_e32 v151, v66
	v_mov_b32_e32 v164, v67
	v_mov_b32_e32 v165, v68
	v_mov_b32_e32 v166, v69
	v_mov_b32_e32 v167, v70
	v_mov_b32_e32 v186, v71
	v_mov_b32_e32 v187, v72
	v_mov_b32_e32 v188, v73
	v_mov_b32_e32 v189, v74
	v_mov_b32_e32 v190, v75
	v_mov_b32_e32 v191, v76
	v_mov_b32_e32 v192, v77
	v_mov_b32_e32 v193, v78
	v_mov_b32_e32 v148, v79
	v_exp_f32_e32 v194, v80
	v_exp_f32_e32 v195, v81
	v_exp_f32_e32 v221, v82
	v_exp_f32_e32 v222, v83
	v_exp_f32_e32 v223, v84
	v_exp_f32_e32 v224, v85
	v_exp_f32_e32 v225, v86
	v_exp_f32_e32 v226, v87
	v_exp_f32_e32 v227, v88
	v_exp_f32_e32 v228, v89
	v_exp_f32_e32 v229, v90
	v_exp_f32_e32 v230, v91
	v_exp_f32_e32 v231, v92
	v_exp_f32_e32 v232, v93
	v_exp_f32_e32 v233, v94
	v_exp_f32_e32 v234, v95
	s_waitcnt lgkmcnt(0)
	s_barrier
	v_add_u32_e32 v68, v141, v137
	ds_read_b128 v[64:67], v68
	ds_read_b128 v[68:71], v68 offset:4096
	v_add_u32_e32 v140, v141, v138
	ds_read_b128 v[136:139], v140
	ds_read_b128 v[142:145], v140 offset:4096
	v_add_u32_e32 v140, v141, v146
	s_waitcnt vmcnt(0)
	s_mul_hi_u32 s0, s64, 0xaaaaaaab
	s_lshr_b32 s0, s0, 1
	s_mul_i32 s1, s0, 0x6000
	s_mul_i32 s0, s0, 0xc000
	v_subrev_u32_e32 v72, s0, v210
	v_add_u32_e32 v72, v217, v72
	ds_write_b128 v72, v[124:127]
	v_subrev_u32_e32 v72, s0, v209
	v_add_u32_e32 v72, v217, v72
	ds_write_b128 v72, v[128:131]
	v_subrev_u32_e32 v72, s1, v208
	v_add_u32_e32 v72, s13, v72
	ds_write_b128 v72, v[132:135]
	s_waitcnt lgkmcnt(6)
	v_mfma_f32_32x32x16_bf16 v[80:95], v[64:67], v[108:111], v[236:251]
	v_exp_f32_e32 v146, v151
	v_exp_f32_e32 v151, v167
	v_exp_f32_e32 v167, v189
	v_exp_f32_e32 v189, v193
	s_waitcnt lgkmcnt(5)
	v_mfma_f32_32x32x16_bf16 v[64:79], v[68:71], v[108:111], v[236:251]
	s_waitcnt lgkmcnt(4)
	v_mfma_f32_32x32x16_bf16 v[80:95], v[136:139], v[104:107], v[80:95]
	s_waitcnt lgkmcnt(3)
	v_mfma_f32_32x32x16_bf16 v[64:79], v[142:145], v[104:107], v[64:79]
	ds_read_b128 v[136:139], v140
	ds_read_b128 v[142:145], v140 offset:4096
	v_add_u32_e32 v140, v141, v147
	v_exp_f32_e32 v147, v164
	v_exp_f32_e32 v164, v186
	v_exp_f32_e32 v186, v190
	v_exp_f32_e32 v190, v148
	s_waitcnt lgkmcnt(1)
	v_mfma_f32_32x32x16_bf16 v[80:95], v[136:139], v[100:103], v[80:95]
	s_waitcnt lgkmcnt(0)
	v_mfma_f32_32x32x16_bf16 v[64:79], v[142:145], v[100:103], v[64:79]
	ds_read_b128 v[136:139], v140
	ds_read_b128 v[140:143], v140 offset:4096
	v_exp_f32_e32 v144, v149
	v_exp_f32_e32 v145, v150
	v_exp_f32_e32 v149, v165
	v_exp_f32_e32 v150, v166
	v_exp_f32_e32 v165, v187
	v_exp_f32_e32 v166, v188
	s_waitcnt lgkmcnt(1)
	v_mfma_f32_32x32x16_bf16 v[80:95], v[136:139], v[96:99], v[80:95]
	v_add_f32_e32 v136, v195, v194
	v_mov_b32_e32 v219, v221
	v_add_f32_e32 v136, v222, v136
	v_add_f32_e32 v219, v223, v219
	v_add_f32_e32 v136, v224, v136
	v_add_f32_e32 v219, v225, v219
	v_add_f32_e32 v136, v226, v136
	v_add_f32_e32 v219, v227, v219
	v_add_f32_e32 v136, v228, v136
	v_add_f32_e32 v219, v229, v219
	v_add_f32_e32 v136, v230, v136
	v_add_f32_e32 v219, v231, v219
	v_add_f32_e32 v136, v232, v136
	v_add_f32_e32 v219, v233, v219
	v_add_f32_e32 v136, v234, v136
	v_add_f32_e32 v219, v144, v219
	v_add_f32_e32 v136, v145, v136
	v_add_f32_e32 v219, v146, v219
	v_add_f32_e32 v136, v147, v136
	v_add_f32_e32 v219, v149, v219
	v_add_f32_e32 v136, v150, v136
	v_add_f32_e32 v219, v151, v219
	v_add_f32_e32 v136, v164, v136
	v_exp_f32_e32 v187, v191
	v_add_f32_e32 v219, v165, v219
	v_exp_f32_e32 v188, v192
	v_add_f32_e32 v136, v166, v136
	s_waitcnt lgkmcnt(0)
	v_mfma_f32_32x32x16_bf16 v[64:79], v[140:143], v[96:99], v[64:79]
	v_add_f32_e32 v219, v167, v219
	v_add_f32_e32 v136, v186, v136
	v_add_f32_e32 v219, v187, v219
	v_add_f32_e32 v136, v188, v136
	v_add_f32_e32 v219, v189, v219
	v_add_f32_e32 v136, v190, v136
	v_add_f32_e32 v219, v219, v136
	v_mov_b32_e32 v220, v219
	v_cvt_pk_bf16_f32 v136, v194, v195
	v_cvt_pk_bf16_f32 v137, v221, v222
	v_cvt_pk_bf16_f32 v138, v223, v224
	v_cvt_pk_bf16_f32 v139, v225, v226
	v_cvt_pk_bf16_f32 v140, v227, v228
	v_cvt_pk_bf16_f32 v141, v229, v230
	v_cvt_pk_bf16_f32 v142, v231, v232
	v_cvt_pk_bf16_f32 v143, v233, v234
	v_cvt_pk_bf16_f32 v144, v144, v145
	v_cvt_pk_bf16_f32 v145, v146, v147
	v_cvt_pk_bf16_f32 v146, v149, v150
	v_cvt_pk_bf16_f32 v147, v151, v164
	v_cvt_pk_bf16_f32 v148, v165, v166
	v_cvt_pk_bf16_f32 v149, v167, v186
	v_cvt_pk_bf16_f32 v150, v187, v188
	v_cvt_pk_bf16_f32 v151, v189, v190
	s_nop 1
	v_permlane32_swap_b32_e32 v219, v220
	v_permlane32_swap_b32_e32 v136, v138
	v_permlane32_swap_b32_e32 v137, v139
	v_permlane32_swap_b32_e32 v140, v142
	v_permlane32_swap_b32_e32 v141, v143
	v_permlane32_swap_b32_e32 v144, v146
	v_permlane32_swap_b32_e32 v145, v147
	v_permlane32_swap_b32_e32 v148, v150
	v_permlane32_swap_b32_e32 v149, v151
	s_cmp_ge_u32 s48, s44
	s_cselect_b64 s[10:11], -1, 0
	s_and_b64 vcc, exec, s[10:11]
	s_cbranch_vccnz .LBB0_96
	v_add_co_u32_e32 v112, vcc, 0x1a810000, v168
	s_nop 1
	v_addc_co_u32_e32 v113, vcc, 0, v169, vcc
	v_add_co_u32_e32 v114, vcc, 0x1a812000, v168
	s_nop 1
	v_addc_co_u32_e32 v115, vcc, 0, v169, vcc
	v_add_co_u32_e32 v120, vcc, 0x18690000, v170
	global_load_dwordx4 v[116:119], v[112:113], off
	s_nop 0
	global_load_dwordx4 v[112:115], v[114:115], off
	v_addc_co_u32_e32 v121, vcc, 0, v171, vcc
	global_load_dwordx4 v[120:123], v[120:121], off
